# v15: v12 + mixer K/V staging address rewrite (three 32-bit row offsets + scalar base instead of six divide/64-bit-mad chains) + 24-bit multiplies in the mixer staging
# speedup vs baseline: 1.0010x; 1.0010x over previous
.LBB0_502:
	s_or_b64 exec, exec, s[12:13]
	s_waitcnt vmcnt(24)
	v_mov_b32_e32 v7, v0
	s_mov_b64 s[2:3], s[0:1]
	s_barrier
	s_load_dwordx2 s[2:3], s[2:3], 0x98
	s_lshl_b32 s6, s44, 2
	s_add_i32 s7, s6, s8
	v_and_b32_e32 v6, 63, v7
	v_readfirstlane_b32 s6, v7
	s_waitcnt lgkmcnt(0)
	s_add_u32 s12, s2, 0x4a00000
	s_addc_u32 s13, s3, 0
	s_ashr_i32 s16, s7, 7
	s_lshl_b32 s7, s7, 6
	s_ashr_i32 s17, s16, 31
	s_and_b32 s14, s7, 0x1fc0
	s_lshl_b64 s[66:67], s[16:17], 13
	s_or_b32 s68, s66, s14
	s_mov_b32 s69, s67
	s_lshr_b64 s[18:19], s[68:69], 8
	s_mul_hi_u32 s16, s18, 0x1a0000
	s_mul_i32 s17, s17, 0x1a0000
	s_mul_i32 s15, s18, 0x1a0000
	s_add_i32 s17, s16, s17
	s_add_u32 s16, s12, s15
	v_mov_b32_e32 v1, s7
	s_movk_i32 s15, 0xdf
	v_bitop3_b32 v1, v6, s15, v1 bitop3:0xc8
	s_addc_u32 s17, s13, s17
	v_mul_u32_u24_e32 v2, 0x1200, v1
	s_and_b32 s72, s6, 0xffffffc0
	v_lshl_add_u64 v[4:5], s[16:17], 0, v[2:3]
	s_ashr_i32 s73, s72, 31
	v_bfe_u32 v8, v7, 5, 1
	s_mov_b32 s19, 0x2aaaaaab
	v_lshl_add_u64 v[4:5], s[72:73], 1, v[4:5]
	v_lshlrev_b32_e32 v2, 4, v8
	v_mul_hi_i32 v1, v7, s19
	s_waitcnt vmcnt(20)
	v_lshl_add_u64 v[10:11], v[4:5], 0, v[2:3]
	v_ashrrev_i32_e32 v2, 8, v1
	s_waitcnt vmcnt(16)
	v_lshrrev_b32_e32 v15, 31, v1
	v_add_u32_e32 v67, v2, v15
	s_mov_b64 s[2:3], s[0:1]
	v_mul_i32_i24_e32 v2, 0x600, v67
	v_sub_u32_e32 v9, v7, v2
	s_load_dwordx2 s[74:75], s[2:3], 0x8
	s_mov_b64 s[2:3], s[0:1]
	s_add_i32 s15, s14, 0xffffff80
	v_ashrrev_i32_e32 v71, 3, v9
	v_add_u32_e32 v2, s15, v71
	s_load_dwordx2 s[8:9], s[2:3], 0x48
	s_mov_b64 s[2:3], s[0:1]
	v_max_i32_e32 v2, 0, v2
	global_load_dwordx4 v[112:115], v[10:11], off
	global_load_dwordx4 v[104:107], v[10:11], off offset:32
	global_load_dwordx4 v[108:111], v[10:11], off offset:64
	global_load_dwordx4 v[100:103], v[10:11], off offset:96
	s_waitcnt vmcnt(4)
	v_add_u32_e32 v12, 0x200, v7
	v_add_u32_e32 v9, 0x400, v7
	v_mul_hi_i32 v13, v12, s19
	v_mul_hi_i32 v10, v9, s19
	v_lshrrev_b32_e32 v14, 31, v13
	v_lshrrev_b32_e32 v11, 31, v10
	v_and_b32_e32 v66, 7, v7
	v_lshlrev_b32_e32 v66, 3, v66
	v_add_u32_e32 v75, 64, v71
	v_add_u32_e32 v79, 0x80, v71
	v_add_u32_e32 v16, s66, v2
	v_lshrrev_b32_e32 v17, 8, v16
	v_and_b32_e32 v16, 0xff, v16
	v_mul_u32_u24_e32 v17, 0x1a0000, v17
	v_mad_u32_u24 v17, v16, s60, v17
	v_lshl_add_u32 v85, v66, 1, v17
	v_add_u32_e32 v16, s15, v75
	v_max_i32_e32 v16, 0, v16
	v_add_u32_e32 v16, s66, v16
	v_lshrrev_b32_e32 v17, 8, v16
	v_and_b32_e32 v16, 0xff, v16
	v_mul_u32_u24_e32 v17, 0x1a0000, v17
	v_mad_u32_u24 v17, v16, s60, v17
	v_lshl_add_u32 v88, v66, 1, v17
	v_add_u32_e32 v16, s15, v79
	v_max_i32_e32 v16, 0, v16
	v_add_u32_e32 v16, s66, v16
	v_lshrrev_b32_e32 v17, 8, v16
	v_and_b32_e32 v16, 0xff, v16
	v_mul_u32_u24_e32 v17, 0x1a0000, v17
	v_mad_u32_u24 v17, v16, s60, v17
	v_lshl_add_u32 v89, v66, 1, v17
	v_mov_b32_e32 v70, v66
	v_mov_b32_e32 v74, v66
	v_mov_b32_e32 v78, v66
	v_mov_b32_e32 v82, v66
	v_mov_b32_e32 v86, v66
	v_mov_b32_e32 v83, v71
	v_mov_b32_e32 v87, v75
	v_mov_b32_e32 v90, v79
	v_mov_b32_e32 v65, 0
	v_mov_b32_e32 v69, 0
	v_mov_b32_e32 v64, 0
	v_mov_b32_e32 v68, 0
	v_mov_b32_e32 v72, 0
	v_mov_b32_e32 v73, 1
	v_mov_b32_e32 v77, 1
	v_mov_b32_e32 v81, 1
	v_mov_b32_e32 v76, 64
	v_mov_b32_e32 v80, 64
	v_mov_b32_e32 v84, 64
	global_load_dwordx4 v[16:19], v85, s[12:13] offset:1024
	global_load_dwordx4 v[20:23], v85, s[12:13] offset:1280
	global_load_dwordx4 v[24:27], v88, s[12:13] offset:1024
	global_load_dwordx4 v[28:31], v88, s[12:13] offset:1280
	global_load_dwordx4 v[32:35], v89, s[12:13] offset:1024
	global_load_dwordx4 v[36:39], v89, s[12:13] offset:1280
	global_load_dwordx4 v[40:43], v85, s[12:13] offset:1152
	global_load_dwordx4 v[44:47], v85, s[12:13] offset:1408
	global_load_dwordx4 v[48:51], v88, s[12:13] offset:1152
	global_load_dwordx4 v[52:55], v88, s[12:13] offset:1408
	global_load_dwordx4 v[56:59], v89, s[12:13] offset:1152
	global_load_dwordx4 v[60:63], v89, s[12:13] offset:1408
	s_load_dwordx2 s[70:71], s[2:3], 0x40
	s_movk_i32 s16, 0xc0
	v_mad_i32_i24 v2, v67, s16, v71
	v_mad_u32_u24 v88, v2, s43, v66
	v_lshl_add_u32 v2, v88, 1, 0
	s_waitcnt vmcnt(11)
	ds_write_b128 v2, v[16:19]
	v_or_b32_e32 v2, v66, v64
	s_movk_i32 s15, 0x190
	v_mul_u32_u24_e32 v2, s15, v2
	v_lshlrev_b32_e32 v16, 1, v71
	v_add3_u32 v2, 0, v2, v16
	s_waitcnt vmcnt(10)
	ds_write_b16 v2, v20 offset:55296
	ds_write_b16_d16_hi v2, v20 offset:55696
	ds_write_b16 v2, v21 offset:56096
	ds_write_b16_d16_hi v2, v21 offset:56496
	ds_write_b16 v2, v22 offset:56896
	ds_write_b16_d16_hi v2, v22 offset:57296
	ds_write_b16 v2, v23 offset:57696
	ds_write_b16_d16_hi v2, v23 offset:58096
	v_mad_i32_i24 v2, v65, s16, v75
	v_mad_u32_u24 v16, v2, s43, v70
	v_lshl_add_u32 v2, v16, 1, 0
	s_waitcnt vmcnt(9)
	ds_write_b128 v2, v[24:27]
	v_or_b32_e32 v2, v70, v68
	v_mul_u32_u24_e32 v2, s15, v2
	v_lshlrev_b32_e32 v16, 1, v75
	v_add3_u32 v2, 0, v2, v16
	s_waitcnt vmcnt(8)
	ds_write_b16 v2, v28 offset:55296
	ds_write_b16_d16_hi v2, v28 offset:55696
	ds_write_b16 v2, v29 offset:56096
	ds_write_b16_d16_hi v2, v29 offset:56496
	ds_write_b16 v2, v30 offset:56896
	ds_write_b16_d16_hi v2, v30 offset:57296
	ds_write_b16 v2, v31 offset:57696
	ds_write_b16_d16_hi v2, v31 offset:58096
	v_mad_i32_i24 v2, v69, s16, v79
	v_mad_u32_u24 v16, v2, s43, v74
	v_lshl_add_u32 v2, v16, 1, 0
	s_waitcnt vmcnt(7)
	ds_write_b128 v2, v[32:35]
	v_or_b32_e32 v2, v74, v72
	v_mul_u32_u24_e32 v2, s15, v2
	v_lshlrev_b32_e32 v16, 1, v79
	v_add3_u32 v2, 0, v2, v16
	s_waitcnt vmcnt(6)
	ds_write_b16 v2, v36 offset:55296
	ds_write_b16_d16_hi v2, v36 offset:55696
	ds_write_b16 v2, v37 offset:56096
	ds_write_b16_d16_hi v2, v37 offset:56496
	ds_write_b16 v2, v38 offset:56896
	ds_write_b16_d16_hi v2, v38 offset:57296
	ds_write_b16 v2, v39 offset:57696
	ds_write_b16_d16_hi v2, v39 offset:58096
	v_mad_i32_i24 v2, v73, s16, v83
	v_mad_u32_u24 v16, v2, s43, v78
	v_lshl_add_u32 v2, v16, 1, 0
	s_waitcnt vmcnt(5)
	ds_write_b128 v2, v[40:43]
	v_or_b32_e32 v2, v78, v76
	v_mul_u32_u24_e32 v2, s15, v2
	v_lshlrev_b32_e32 v16, 1, v83
	v_add3_u32 v2, 0, v2, v16
	s_waitcnt vmcnt(4)
	ds_write_b16 v2, v44 offset:55296
	ds_write_b16_d16_hi v2, v44 offset:55696
	ds_write_b16 v2, v45 offset:56096
	ds_write_b16_d16_hi v2, v45 offset:56496
	ds_write_b16 v2, v46 offset:56896
	ds_write_b16_d16_hi v2, v46 offset:57296
	ds_write_b16 v2, v47 offset:57696
	ds_write_b16_d16_hi v2, v47 offset:58096
	v_mad_i32_i24 v2, v77, s16, v87
	v_mad_u32_u24 v16, v2, s43, v82
	v_lshl_add_u32 v2, v16, 1, 0
	s_waitcnt vmcnt(3)
	ds_write_b128 v2, v[48:51]
	v_or_b32_e32 v2, v82, v80
	v_mul_u32_u24_e32 v2, s15, v2
	v_lshlrev_b32_e32 v16, 1, v87
	v_add3_u32 v2, 0, v2, v16
	s_waitcnt vmcnt(2)
	ds_write_b16 v2, v52 offset:55296
	ds_write_b16_d16_hi v2, v52 offset:55696
	ds_write_b16 v2, v53 offset:56096
	ds_write_b16_d16_hi v2, v53 offset:56496
	ds_write_b16 v2, v54 offset:56896
	ds_write_b16_d16_hi v2, v54 offset:57296
	ds_write_b16 v2, v55 offset:57696
	ds_write_b16_d16_hi v2, v55 offset:58096
	v_mad_i32_i24 v2, v81, s16, v90
	v_mad_u32_u24 v16, v2, s43, v86
	v_lshl_add_u32 v2, v16, 1, 0
	s_waitcnt vmcnt(1)
	ds_write_b128 v2, v[56:59]
	v_or_b32_e32 v2, v86, v84
	v_mul_u32_u24_e32 v2, s15, v2
	v_lshlrev_b32_e32 v16, 1, v90
	v_ashrrev_i32_e32 v1, 5, v1
	v_add3_u32 v2, 0, v2, v16
	v_add_u32_e32 v1, v1, v15
	s_waitcnt vmcnt(0)
	ds_write_b16 v2, v60 offset:55296
	ds_write_b16_d16_hi v2, v60 offset:55696
	ds_write_b16 v2, v61 offset:56096
	ds_write_b16_d16_hi v2, v61 offset:56496
	ds_write_b16 v2, v62 offset:56896
	ds_write_b16_d16_hi v2, v62 offset:57296
	ds_write_b16 v2, v63 offset:57696
	ds_write_b16_d16_hi v2, v63 offset:58096
	v_mul_u32_u24_e32 v2, s16, v1
	v_sub_u32_e32 v16, v7, v2
	v_subrev_u32_e32 v2, 33, v16
	s_movk_i32 s2, 0x80
	s_movk_i32 s15, 0xc0
	v_cmp_gt_u32_e32 vcc, s2, v2
	v_mov_b32_e32 v15, 0xff800000
	s_and_saveexec_b64 s[76:77], vcc
	s_cbranch_execz .LBB0_506
	s_movk_i32 s2, 0x91
	v_sub_u32_e32 v2, 0xa0, v16
	v_cmp_gt_u32_e32 vcc, s2, v16
	s_and_saveexec_b64 s[78:79], vcc
	s_cbranch_execz .LBB0_505
	v_cvt_f32_ubyte0_e32 v2, v2
	v_mul_f32_e32 v2, 0x3d800000, v2
	s_mov_b32 s2, 0x800000
	v_cmp_gt_f32_e32 vcc, s2, v2
	s_mov_b32 s2, 0x3f317217
	s_nop 0
	v_cndmask_b32_e64 v15, 0, 32, vcc
	v_ldexp_f32 v2, v2, v15
	v_log_f32_e32 v2, v2
	s_nop 0
	v_mul_f32_e32 v15, 0x3f317217, v2
	v_fma_f32 v15, v2, s2, -v15
	v_fmac_f32_e32 v15, 0x3377d1cf, v2
	s_mov_b32 s2, 0x7f800000
	v_fmac_f32_e32 v15, 0x3f317217, v2
	v_cmp_lt_f32_e64 s[2:3], |v2|, s2
	s_nop 1
	v_cndmask_b32_e64 v2, v2, v15, s[2:3]
	v_mov_b32_e32 v15, 0x41b17218
	v_cndmask_b32_e32 v15, 0, v15, vcc
	v_sub_f32_e32 v2, v2, v15
	v_mul_f32_e32 v2, 0x40f6384f, v2
	v_cvt_i32_f32_e32 v2, v2
	v_min_i32_e32 v2, 15, v2
	v_add_u32_e32 v2, 16, v2

.LBB0_506:
	s_or_b64 exec, exec, s[76:77]
	v_ashrrev_i32_e32 v13, 5, v13
	v_add_u32_e32 v13, v13, v14
	v_mul_u32_u24_e32 v14, s15, v13
	v_sub_u32_e32 v14, v12, v14
	v_lshl_add_u32 v2, v7, 2, 0
	v_subrev_u32_e32 v12, 33, v14
	s_movk_i32 s2, 0x80
	v_lshlrev_b32_e32 v1, 3, v8
	v_add_u32_e32 v2, 0x1a000, v2
	v_cmp_gt_u32_e32 vcc, s2, v12
	v_mov_b32_e32 v12, 0xff800000
	ds_write_b32 v2, v15
	s_and_saveexec_b64 s[76:77], vcc
	s_cbranch_execz .LBB0_510
	s_movk_i32 s2, 0x91
	v_sub_u32_e32 v12, 0xa0, v14
	v_cmp_gt_u32_e32 vcc, s2, v14
	s_and_saveexec_b64 s[78:79], vcc
	s_cbranch_execz .LBB0_509
	v_cvt_f32_ubyte0_e32 v12, v12
	v_mul_f32_e32 v12, 0x3d800000, v12
	s_mov_b32 s2, 0x800000
	v_cmp_gt_f32_e32 vcc, s2, v12
	s_mov_b32 s2, 0x3f317217
	s_nop 0
	v_cndmask_b32_e64 v14, 0, 32, vcc
	v_ldexp_f32 v12, v12, v14
	v_log_f32_e32 v12, v12
	s_nop 0
	v_mul_f32_e32 v14, 0x3f317217, v12
	v_fma_f32 v14, v12, s2, -v14
	v_fmac_f32_e32 v14, 0x3377d1cf, v12
	s_mov_b32 s2, 0x7f800000
	v_fmac_f32_e32 v14, 0x3f317217, v12
	v_cmp_lt_f32_e64 s[2:3], |v12|, s2
	s_nop 1
	v_cndmask_b32_e64 v12, v12, v14, s[2:3]
	v_mov_b32_e32 v14, 0x41b17218
	v_cndmask_b32_e32 v14, 0, v14, vcc
	v_sub_f32_e32 v12, v12, v14
	v_mul_f32_e32 v12, 0x40f6384f, v12
	v_cvt_i32_f32_e32 v12, v12
	v_min_i32_e32 v12, 15, v12
	v_add_u32_e32 v12, 16, v12

.LBB0_510:
	s_or_b64 exec, exec, s[76:77]
	v_ashrrev_i32_e32 v10, 5, v10
	v_add_u32_e32 v10, v10, v11
	v_mul_u32_u24_e32 v11, s15, v10
	v_sub_u32_e32 v11, v9, v11
	v_subrev_u32_e32 v9, 33, v11
	s_movk_i32 s2, 0x80
	v_cmp_gt_u32_e32 vcc, s2, v9
	v_mov_b32_e32 v9, 0xff800000
	ds_write_b32 v2, v12 offset:2048
	s_and_saveexec_b64 s[76:77], vcc
	s_cbranch_execz .LBB0_514
	s_movk_i32 s2, 0x91
	v_sub_u32_e32 v9, 0xa0, v11
	v_cmp_gt_u32_e32 vcc, s2, v11
	s_and_saveexec_b64 s[78:79], vcc
	s_cbranch_execz .LBB0_513
	v_cvt_f32_ubyte0_e32 v9, v9
	v_mul_f32_e32 v9, 0x3d800000, v9
	s_mov_b32 s2, 0x800000
	v_cmp_gt_f32_e32 vcc, s2, v9
	s_mov_b32 s2, 0x3f317217
	s_nop 0
	v_cndmask_b32_e64 v11, 0, 32, vcc
	v_ldexp_f32 v9, v9, v11
	v_log_f32_e32 v9, v9
	s_nop 0
	v_mul_f32_e32 v11, 0x3f317217, v9
	v_fma_f32 v11, v9, s2, -v11
	v_fmac_f32_e32 v11, 0x3377d1cf, v9
	s_mov_b32 s2, 0x7f800000
	v_fmac_f32_e32 v11, 0x3f317217, v9
	v_cmp_lt_f32_e64 s[2:3], |v9|, s2
	s_nop 1
	v_cndmask_b32_e64 v9, v9, v11, s[2:3]
	v_mov_b32_e32 v11, 0x41b17218
	v_cndmask_b32_e32 v11, 0, v11, vcc
	v_sub_f32_e32 v9, v9, v11
	v_mul_f32_e32 v9, 0x40f6384f, v9
	v_cvt_i32_f32_e32 v9, v9
	v_min_i32_e32 v9, 15, v9
	v_add_u32_e32 v9, 16, v9
